# mix2 S=QK^T section: K-row LDS reads of a column block issued before the previous block's exp/mask/convert work instead of after it
# baseline (speedup 1.0000x reference)
; #define LAS __attribute__((address_space(3)))
; __device__ __forceinline__ unsigned cvt_pk_bf16(float lo, float hi) { unsigned r; asm volatile("v_cvt_pk_bf16_f32 %0, %1, %2" : "=v"(r) : "v"(lo), "v"(hi)); return r; }
; #define MFMA16(a, b, c) __builtin_amdgcn_mfma_f32_16x16x32_bf16((a), (b), (c), 0, 0, 0)
; __device__ void mix_sweep(const Params& P, LAS unsigned char* lds, int tok0, int pos0, int seqlen, int hd, int dir, bool state_only, bool final_pass,
;                           f32x4 (&Cacc)[9], float& m_state, float& aseg_sum, float lgam) {
;     ...
;             for (int nt = 0; nt < 8; ++nt) { f32x4 a = (f32x4){0.f, 0.f, 0.f, 0.f}; bf16x8 kr[4];
; #pragma unroll
;                 for (int s = 0; s < 4; ++s) kr[s] = ROWFRAG(IMG_K, 16 * nt, s);
;                 __builtin_amdgcn_sched_barrier(0);
; #pragma unroll
;                 for (int s = 0; s < 4; ++s) a = MFMA16(kr[s], qf[s], a);
;                 const f32x4 ct = *(const LAS f32x4*)(vcol + 16 * nt + 4 * fg); float p[4];
; #pragma unroll
;                 for (int e = 0; e < 4; ++e) { const int j = 16 * nt + 4 * fg + e;
;                     const bool keep = dir ? (is_m ? (j >= irow) : (j > irow)) : (j <= irow);
;                     const float ex = __builtin_amdgcn_exp2f(rt + ct[e]); p[e] = keep ? a[e] * ex : 0.f; }
;                 u32x2 pv; pv.x = cvt_pk_bf16(p[0], p[1]); pv.y = cvt_pk_bf16(p[2], p[3]);
;                 { LAUNDER_X16 *(LAS u32x2*)(lds + IMG_Q + CWA(nt)) = pv; } __builtin_amdgcn_sched_barrier(0); }
.Lmk_done_0:
.LBB0_139:
	s_waitcnt lgkmcnt(0)
	ds_read_b128 v[222:225], v132 offset:36864
	ds_read_b128 v[226:229], v133 offset:36864
	ds_read_b128 v[230:233], v134 offset:36864
	ds_read_b128 v[234:237], v135 offset:36864
	v_add_f32_e32 v126, v171, v126
	v_add_f32_e32 v125, v171, v125
	v_add_f32_e32 v124, v171, v124
	v_exp_f32_e32 v126, v126
	v_exp_f32_e32 v125, v125
	v_exp_f32_e32 v124, v124
	v_add_f32_e32 v127, v171, v127
	v_exp_f32_e32 v127, v127
	v_mul_f32_e32 v126, v130, v126
	v_mul_f32_e32 v125, v129, v125
	v_mul_f32_e32 v124, v128, v124
	v_cndmask_b32_e64 v126, 0, v126, s[50:51]
	v_cndmask_b32_e64 v125, 0, v125, s[18:19]
	v_cndmask_b32_e64 v124, 0, v124, s[16:17]
	v_mul_f32_e32 v127, v131, v127
	v_cndmask_b32_e64 v127, 0, v127, s[54:55]
	v_cvt_pk_bf16_f32 v124, v124, v125
	v_cvt_pk_bf16_f32 v125, v126, v127
	v_mov_b32_e32 v126, v179
	s_nop 0
	v_add_u32_e32 v126, v191, v126
	ds_write_b64 v126, v[124:125]
	s_waitcnt lgkmcnt(4)
	v_mfma_f32_16x16x32_bf16 v[124:127], v[222:225], v[92:95], 0
	s_mov_b64 s[18:19], -1
	s_and_b64 vcc, exec, s[48:49]
	s_waitcnt lgkmcnt(3)
	v_mfma_f32_16x16x32_bf16 v[124:127], v[226:229], v[96:99], v[124:127]
	ds_read_b128 v[128:131], v190 offset:64
	s_waitcnt lgkmcnt(3)
	v_mfma_f32_16x16x32_bf16 v[124:127], v[230:233], v[100:103], v[124:127]
	s_waitcnt lgkmcnt(2)
	v_mfma_f32_16x16x32_bf16 v[124:127], v[234:237], v[88:91], v[124:127]
	v_or_b32_e32 v136, 16, v189
	v_or_b32_e32 v137, 17, v189
	v_or_b32_e32 v138, 18, v189
	v_or_b32_e32 v139, 19, v189
	v_cmp_le_i32_e64 s[16:17], v136, v188
	v_cmp_le_i32_e64 s[18:19], v137, v188
	v_cmp_le_i32_e64 s[50:51], v138, v188
	v_cmp_le_i32_e64 s[54:55], v139, v188
	s_cbranch_vccnz .Lmk_done_1
	v_cndmask_b32_e64 v140, 1, 0, s[42:43]
	v_add_u32_e32 v140, v140, v188
	v_cmp_ge_i32_e64 s[16:17], v136, v140
	v_cmp_ge_i32_e64 s[18:19], v137, v140
	v_cmp_ge_i32_e64 s[50:51], v138, v140
	v_cmp_ge_i32_e64 s[54:55], v139, v140
.Lmk_done_1:
.LBB0_171:
	s_waitcnt lgkmcnt(0)
	ds_read_b128 v[222:225], v132 offset:40960
	ds_read_b128 v[226:229], v133 offset:40960
	ds_read_b128 v[230:233], v134 offset:40960
	ds_read_b128 v[234:237], v135 offset:40960
	v_add_f32_e32 v129, v171, v129
	v_exp_f32_e32 v129, v129
	v_add_f32_e32 v130, v171, v130
	v_add_f32_e32 v128, v171, v128
	v_exp_f32_e32 v130, v130
	v_mul_f32_e32 v125, v125, v129
	v_exp_f32_e32 v128, v128
	v_add_f32_e32 v129, v171, v131
	v_exp_f32_e32 v129, v129
	v_mul_f32_e32 v126, v126, v130
	v_mul_f32_e32 v124, v124, v128
	v_cndmask_b32_e64 v126, 0, v126, s[50:51]
	v_cndmask_b32_e64 v125, 0, v125, s[18:19]
	v_cndmask_b32_e64 v124, 0, v124, s[16:17]
	v_mul_f32_e32 v127, v127, v129
	v_cndmask_b32_e64 v127, 0, v127, s[54:55]
	v_cvt_pk_bf16_f32 v124, v124, v125
	v_cvt_pk_bf16_f32 v125, v126, v127
	v_mov_b32_e32 v126, v179
	s_nop 0
	v_xad_u32 v126, v126, 32, v191
	ds_write_b64 v126, v[124:125]
	s_waitcnt lgkmcnt(4)
	v_mfma_f32_16x16x32_bf16 v[124:127], v[222:225], v[92:95], 0
	s_mov_b64 s[18:19], -1
	s_and_b64 vcc, exec, s[48:49]
	s_waitcnt lgkmcnt(3)
	v_mfma_f32_16x16x32_bf16 v[124:127], v[226:229], v[96:99], v[124:127]
	ds_read_b128 v[128:131], v190 offset:128
	s_waitcnt lgkmcnt(3)
	v_mfma_f32_16x16x32_bf16 v[124:127], v[230:233], v[100:103], v[124:127]
	s_waitcnt lgkmcnt(2)
	v_mfma_f32_16x16x32_bf16 v[124:127], v[234:237], v[88:91], v[124:127]
	v_or_b32_e32 v136, 32, v189
	v_or_b32_e32 v137, 33, v189
	v_or_b32_e32 v138, 34, v189
	v_or_b32_e32 v139, 35, v189
	v_cmp_le_i32_e64 s[16:17], v136, v188
	v_cmp_le_i32_e64 s[18:19], v137, v188
	v_cmp_le_i32_e64 s[50:51], v138, v188
	v_cmp_le_i32_e64 s[54:55], v139, v188
	s_cbranch_vccnz .Lmk_done_2
	v_cndmask_b32_e64 v140, 1, 0, s[42:43]
	v_add_u32_e32 v140, v140, v188
	v_cmp_ge_i32_e64 s[16:17], v136, v140
	v_cmp_ge_i32_e64 s[18:19], v137, v140
	v_cmp_ge_i32_e64 s[50:51], v138, v140
	v_cmp_ge_i32_e64 s[54:55], v139, v140
.Lmk_done_2:
.LBB0_203:
	s_waitcnt lgkmcnt(0)
	ds_read_b128 v[222:225], v132 offset:45056
	ds_read_b128 v[226:229], v133 offset:45056
	ds_read_b128 v[230:233], v134 offset:45056
	ds_read_b128 v[234:237], v135 offset:45056
	v_add_f32_e32 v129, v171, v129
	v_exp_f32_e32 v129, v129
	v_add_f32_e32 v130, v171, v130
	v_add_f32_e32 v128, v171, v128
	v_exp_f32_e32 v130, v130
	v_mul_f32_e32 v125, v125, v129
	v_exp_f32_e32 v128, v128
	v_add_f32_e32 v129, v171, v131
	v_exp_f32_e32 v129, v129
	v_mul_f32_e32 v126, v126, v130
	v_mul_f32_e32 v124, v124, v128
	v_cndmask_b32_e64 v126, 0, v126, s[50:51]
	v_cndmask_b32_e64 v125, 0, v125, s[18:19]
	v_cndmask_b32_e64 v124, 0, v124, s[16:17]
	v_mul_f32_e32 v127, v127, v129
	v_cndmask_b32_e64 v127, 0, v127, s[54:55]
	v_cvt_pk_bf16_f32 v124, v124, v125
	v_cvt_pk_bf16_f32 v125, v126, v127
	v_mov_b32_e32 v126, v179
	s_nop 0
	v_xad_u32 v126, v126, 64, v191
	ds_write_b64 v126, v[124:125]
	s_waitcnt lgkmcnt(4)
	v_mfma_f32_16x16x32_bf16 v[124:127], v[222:225], v[92:95], 0
	s_mov_b64 s[18:19], -1
	s_and_b64 vcc, exec, s[48:49]
	s_waitcnt lgkmcnt(3)
	v_mfma_f32_16x16x32_bf16 v[124:127], v[226:229], v[96:99], v[124:127]
	ds_read_b128 v[128:131], v190 offset:192
	s_waitcnt lgkmcnt(3)
	v_mfma_f32_16x16x32_bf16 v[124:127], v[230:233], v[100:103], v[124:127]
	s_waitcnt lgkmcnt(2)
	v_mfma_f32_16x16x32_bf16 v[124:127], v[234:237], v[88:91], v[124:127]
	v_or_b32_e32 v136, 48, v189
	v_or_b32_e32 v137, 49, v189
	v_or_b32_e32 v138, 50, v189
	v_or_b32_e32 v139, 51, v189
	v_cmp_le_i32_e64 s[16:17], v136, v188
	v_cmp_le_i32_e64 s[18:19], v137, v188
	v_cmp_le_i32_e64 s[50:51], v138, v188
	v_cmp_le_i32_e64 s[54:55], v139, v188
	s_cbranch_vccnz .Lmk_done_3
	v_cndmask_b32_e64 v140, 1, 0, s[42:43]
	v_add_u32_e32 v140, v140, v188
	v_cmp_ge_i32_e64 s[16:17], v136, v140
	v_cmp_ge_i32_e64 s[18:19], v137, v140
	v_cmp_ge_i32_e64 s[50:51], v138, v140
	v_cmp_ge_i32_e64 s[54:55], v139, v140
; #define LAS __attribute__((address_space(3)))
; __device__ __forceinline__ unsigned cvt_pk_bf16(float lo, float hi) { unsigned r; asm volatile("v_cvt_pk_bf16_f32 %0, %1, %2" : "=v"(r) : "v"(lo), "v"(hi)); return r; }
; #define MFMA16(a, b, c) __builtin_amdgcn_mfma_f32_16x16x32_bf16((a), (b), (c), 0, 0, 0)
; __device__ void mix_sweep(const Params& P, LAS unsigned char* lds, int tok0, int pos0, int seqlen, int hd, int dir, bool state_only, bool final_pass,
;                           f32x4 (&Cacc)[9], float& m_state, float& aseg_sum, float lgam) {
;     ...
;             for (int nt = 0; nt < 8; ++nt) { f32x4 a = (f32x4){0.f, 0.f, 0.f, 0.f}; bf16x8 kr[4];
; #pragma unroll
;                 for (int s = 0; s < 4; ++s) kr[s] = ROWFRAG(IMG_K, 16 * nt, s);
;                 __builtin_amdgcn_sched_barrier(0);
; #pragma unroll
;                 for (int s = 0; s < 4; ++s) a = MFMA16(kr[s], qf[s], a);
;                 const f32x4 ct = *(const LAS f32x4*)(vcol + 16 * nt + 4 * fg); float p[4];
; #pragma unroll
;                 for (int e = 0; e < 4; ++e) { const int j = 16 * nt + 4 * fg + e;
;                     const bool keep = dir ? (is_m ? (j >= irow) : (j > irow)) : (j <= irow);
;                     const float ex = __builtin_amdgcn_exp2f(rt + ct[e]); p[e] = keep ? a[e] * ex : 0.f; }
;                 u32x2 pv; pv.x = cvt_pk_bf16(p[0], p[1]); pv.y = cvt_pk_bf16(p[2], p[3]);
;                 { LAUNDER_X16 *(LAS u32x2*)(lds + IMG_Q + CWA(nt)) = pv; } __builtin_amdgcn_sched_barrier(0); }
.Lmk_done_3:
.LBB0_235:
	s_waitcnt lgkmcnt(0)
	ds_read_b128 v[222:225], v132 offset:49152
	ds_read_b128 v[226:229], v133 offset:49152
	ds_read_b128 v[230:233], v134 offset:49152
	ds_read_b128 v[234:237], v135 offset:49152
	v_add_f32_e32 v129, v171, v129
	v_exp_f32_e32 v129, v129
	v_add_f32_e32 v130, v171, v130
	v_add_f32_e32 v128, v171, v128
	v_exp_f32_e32 v130, v130
	v_mul_f32_e32 v125, v125, v129
	v_exp_f32_e32 v128, v128
	v_add_f32_e32 v129, v171, v131
	v_exp_f32_e32 v129, v129
	v_mul_f32_e32 v126, v126, v130
	v_mul_f32_e32 v124, v124, v128
	v_cndmask_b32_e64 v126, 0, v126, s[50:51]
	v_cndmask_b32_e64 v125, 0, v125, s[18:19]
	v_cndmask_b32_e64 v124, 0, v124, s[16:17]
	v_mul_f32_e32 v127, v127, v129
	v_cndmask_b32_e64 v127, 0, v127, s[54:55]
	v_cvt_pk_bf16_f32 v124, v124, v125
	v_cvt_pk_bf16_f32 v125, v126, v127
	v_mov_b32_e32 v126, v179
	s_nop 0
	v_xad_u32 v126, v126, s33, v191
	ds_write_b64 v126, v[124:125]
	s_waitcnt lgkmcnt(4)
	v_mfma_f32_16x16x32_bf16 v[124:127], v[222:225], v[92:95], 0
	s_mov_b64 s[18:19], -1
	s_and_b64 vcc, exec, s[48:49]
	s_waitcnt lgkmcnt(3)
	v_mfma_f32_16x16x32_bf16 v[124:127], v[226:229], v[96:99], v[124:127]
	ds_read_b128 v[128:131], v190 offset:256
	s_waitcnt lgkmcnt(3)
	v_mfma_f32_16x16x32_bf16 v[124:127], v[230:233], v[100:103], v[124:127]
	s_waitcnt lgkmcnt(2)
	v_mfma_f32_16x16x32_bf16 v[124:127], v[234:237], v[88:91], v[124:127]
	v_or_b32_e32 v136, 64, v189
	v_or_b32_e32 v137, 0x41, v189
	v_or_b32_e32 v138, 0x42, v189
	v_or_b32_e32 v139, 0x43, v189
	v_cmp_le_i32_e64 s[16:17], v136, v188
	v_cmp_le_i32_e64 s[18:19], v137, v188
	v_cmp_le_i32_e64 s[50:51], v138, v188
	v_cmp_le_i32_e64 s[54:55], v139, v188
	s_cbranch_vccnz .Lmk_done_4
	v_cndmask_b32_e64 v140, 1, 0, s[42:43]
	v_add_u32_e32 v140, v140, v188
	v_cmp_ge_i32_e64 s[16:17], v136, v140
	v_cmp_ge_i32_e64 s[18:19], v137, v140
	v_cmp_ge_i32_e64 s[50:51], v138, v140
	v_cmp_ge_i32_e64 s[54:55], v139, v140
.Lmk_done_4:
.LBB0_267:
	s_waitcnt lgkmcnt(0)
	ds_read_b128 v[222:225], v132 offset:53248
	ds_read_b128 v[226:229], v133 offset:53248
	ds_read_b128 v[230:233], v134 offset:53248
	ds_read_b128 v[234:237], v135 offset:53248
	v_add_f32_e32 v129, v171, v129
	v_exp_f32_e32 v129, v129
	v_add_f32_e32 v130, v171, v130
	v_add_f32_e32 v128, v171, v128
	v_exp_f32_e32 v130, v130
	v_mul_f32_e32 v125, v125, v129
	v_exp_f32_e32 v128, v128
	v_add_f32_e32 v129, v171, v131
	v_exp_f32_e32 v129, v129
	v_mul_f32_e32 v126, v126, v130
	v_mul_f32_e32 v124, v124, v128
	v_cndmask_b32_e64 v126, 0, v126, s[50:51]
	v_cndmask_b32_e64 v125, 0, v125, s[18:19]
	v_cndmask_b32_e64 v124, 0, v124, s[16:17]
	v_mul_f32_e32 v127, v127, v129
	v_cndmask_b32_e64 v127, 0, v127, s[54:55]
	v_cvt_pk_bf16_f32 v124, v124, v125
	v_cvt_pk_bf16_f32 v125, v126, v127
	v_mov_b32_e32 v126, v179
	s_nop 0
	v_xad_u32 v126, v126, s25, v191
	ds_write_b64 v126, v[124:125]
	s_waitcnt lgkmcnt(4)
	v_mfma_f32_16x16x32_bf16 v[124:127], v[222:225], v[92:95], 0
	s_mov_b64 s[18:19], -1
	s_and_b64 vcc, exec, s[48:49]
	s_waitcnt lgkmcnt(3)
	v_mfma_f32_16x16x32_bf16 v[124:127], v[226:229], v[96:99], v[124:127]
	ds_read_b128 v[128:131], v190 offset:320
	s_waitcnt lgkmcnt(3)
	v_mfma_f32_16x16x32_bf16 v[124:127], v[230:233], v[100:103], v[124:127]
	s_waitcnt lgkmcnt(2)
	v_mfma_f32_16x16x32_bf16 v[124:127], v[234:237], v[88:91], v[124:127]
	v_or_b32_e32 v136, 0x50, v189
	v_or_b32_e32 v137, 0x51, v189
	v_or_b32_e32 v138, 0x52, v189
	v_or_b32_e32 v139, 0x53, v189
	v_cmp_le_i32_e64 s[16:17], v136, v188
	v_cmp_le_i32_e64 s[18:19], v137, v188
	v_cmp_le_i32_e64 s[50:51], v138, v188
	v_cmp_le_i32_e64 s[54:55], v139, v188
	s_cbranch_vccnz .Lmk_done_5
	v_cndmask_b32_e64 v140, 1, 0, s[42:43]
	v_add_u32_e32 v140, v140, v188
	v_cmp_ge_i32_e64 s[16:17], v136, v140
	v_cmp_ge_i32_e64 s[18:19], v137, v140
	v_cmp_ge_i32_e64 s[50:51], v138, v140
	v_cmp_ge_i32_e64 s[54:55], v139, v140
; #define LAS __attribute__((address_space(3)))
; __device__ __forceinline__ unsigned cvt_pk_bf16(float lo, float hi) { unsigned r; asm volatile("v_cvt_pk_bf16_f32 %0, %1, %2" : "=v"(r) : "v"(lo), "v"(hi)); return r; }
; #define MFMA16(a, b, c) __builtin_amdgcn_mfma_f32_16x16x32_bf16((a), (b), (c), 0, 0, 0)
; __device__ void mix_sweep(const Params& P, LAS unsigned char* lds, int tok0, int pos0, int seqlen, int hd, int dir, bool state_only, bool final_pass,
;                           f32x4 (&Cacc)[9], float& m_state, float& aseg_sum, float lgam) {
;     ...
;             for (int nt = 0; nt < 8; ++nt) { f32x4 a = (f32x4){0.f, 0.f, 0.f, 0.f}; bf16x8 kr[4];
; #pragma unroll
;                 for (int s = 0; s < 4; ++s) kr[s] = ROWFRAG(IMG_K, 16 * nt, s);
;                 __builtin_amdgcn_sched_barrier(0);
; #pragma unroll
;                 for (int s = 0; s < 4; ++s) a = MFMA16(kr[s], qf[s], a);
;                 const f32x4 ct = *(const LAS f32x4*)(vcol + 16 * nt + 4 * fg); float p[4];
; #pragma unroll
;                 for (int e = 0; e < 4; ++e) { const int j = 16 * nt + 4 * fg + e;
;                     const bool keep = dir ? (is_m ? (j >= irow) : (j > irow)) : (j <= irow);
;                     const float ex = __builtin_amdgcn_exp2f(rt + ct[e]); p[e] = keep ? a[e] * ex : 0.f; }
;                 u32x2 pv; pv.x = cvt_pk_bf16(p[0], p[1]); pv.y = cvt_pk_bf16(p[2], p[3]);
;                 { LAUNDER_X16 *(LAS u32x2*)(lds + IMG_Q + CWA(nt)) = pv; } __builtin_amdgcn_sched_barrier(0); }
.Lmk_done_5:
.LBB0_299:
	s_waitcnt lgkmcnt(0)
	ds_read_b128 v[222:225], v132 offset:57344
	ds_read_b128 v[226:229], v133 offset:57344
	ds_read_b128 v[230:233], v134 offset:57344
	ds_read_b128 v[234:237], v135 offset:57344
	v_add_f32_e32 v129, v171, v129
	v_exp_f32_e32 v129, v129
	v_add_f32_e32 v130, v171, v130
	v_add_f32_e32 v128, v171, v128
	v_exp_f32_e32 v130, v130
	v_mul_f32_e32 v125, v125, v129
	v_exp_f32_e32 v128, v128
	v_add_f32_e32 v129, v171, v131
	v_exp_f32_e32 v129, v129
	v_mul_f32_e32 v126, v126, v130
	v_mul_f32_e32 v124, v124, v128
	v_cndmask_b32_e64 v126, 0, v126, s[50:51]
	v_cndmask_b32_e64 v125, 0, v125, s[18:19]
	v_cndmask_b32_e64 v124, 0, v124, s[16:17]
	v_mul_f32_e32 v127, v127, v129
	v_cndmask_b32_e64 v127, 0, v127, s[54:55]
	v_cvt_pk_bf16_f32 v124, v124, v125
	v_cvt_pk_bf16_f32 v125, v126, v127
	v_mov_b32_e32 v126, v179
	s_nop 0
	v_xad_u32 v126, v126, s31, v191
	ds_write_b64 v126, v[124:125]
	s_waitcnt lgkmcnt(4)
	v_mfma_f32_16x16x32_bf16 v[124:127], v[222:225], v[92:95], 0
	s_mov_b64 s[18:19], -1
	s_and_b64 vcc, exec, s[48:49]
	s_waitcnt lgkmcnt(3)
	v_mfma_f32_16x16x32_bf16 v[124:127], v[226:229], v[96:99], v[124:127]
	ds_read_b128 v[128:131], v190 offset:384
	s_waitcnt lgkmcnt(3)
	v_mfma_f32_16x16x32_bf16 v[124:127], v[230:233], v[100:103], v[124:127]
	s_waitcnt lgkmcnt(2)
	v_mfma_f32_16x16x32_bf16 v[124:127], v[234:237], v[88:91], v[124:127]
	v_or_b32_e32 v136, 0x60, v189
	v_or_b32_e32 v137, 0x61, v189
	v_or_b32_e32 v138, 0x62, v189
	v_or_b32_e32 v139, 0x63, v189
	v_cmp_le_i32_e64 s[16:17], v136, v188
	v_cmp_le_i32_e64 s[18:19], v137, v188
	v_cmp_le_i32_e64 s[50:51], v138, v188
	v_cmp_le_i32_e64 s[54:55], v139, v188
	s_cbranch_vccnz .Lmk_done_6
	v_cndmask_b32_e64 v140, 1, 0, s[42:43]
	v_add_u32_e32 v140, v140, v188
	v_cmp_ge_i32_e64 s[16:17], v136, v140
	v_cmp_ge_i32_e64 s[18:19], v137, v140
	v_cmp_ge_i32_e64 s[50:51], v138, v140
	v_cmp_ge_i32_e64 s[54:55], v139, v140
.Lmk_done_6:
.LBB0_331:
	s_waitcnt lgkmcnt(0)
	ds_read_b128 v[222:225], v132 offset:61440
	ds_read_b128 v[226:229], v133 offset:61440
	ds_read_b128 v[230:233], v134 offset:61440
	ds_read_b128 v[234:237], v135 offset:61440
	v_add_f32_e32 v129, v171, v129
	v_exp_f32_e32 v129, v129
	v_add_f32_e32 v130, v171, v130
	v_add_f32_e32 v128, v171, v128
	v_exp_f32_e32 v130, v130
	v_mul_f32_e32 v125, v125, v129
	v_exp_f32_e32 v128, v128
	v_add_f32_e32 v129, v171, v131
	v_exp_f32_e32 v129, v129
	v_mul_f32_e32 v126, v126, v130
	v_mul_f32_e32 v124, v124, v128
	v_cndmask_b32_e64 v126, 0, v126, s[50:51]
	v_cndmask_b32_e64 v125, 0, v125, s[18:19]
	v_cndmask_b32_e64 v124, 0, v124, s[16:17]
	v_mul_f32_e32 v127, v127, v129
	v_cndmask_b32_e64 v127, 0, v127, s[54:55]
	v_cvt_pk_bf16_f32 v124, v124, v125
	v_cvt_pk_bf16_f32 v125, v126, v127
	v_mov_b32_e32 v126, v179
	s_nop 0
	v_xad_u32 v126, v126, s27, v191
	ds_write_b64 v126, v[124:125]
	s_waitcnt lgkmcnt(4)
	v_mfma_f32_16x16x32_bf16 v[92:95], v[222:225], v[92:95], 0
	s_mov_b64 s[18:19], -1
	s_and_b64 vcc, exec, s[48:49]
	s_waitcnt lgkmcnt(3)
	v_mfma_f32_16x16x32_bf16 v[92:95], v[226:229], v[96:99], v[92:95]
	s_waitcnt lgkmcnt(2)
	v_mfma_f32_16x16x32_bf16 v[96:99], v[230:233], v[100:103], v[92:95]
	s_waitcnt lgkmcnt(1)
	v_mfma_f32_16x16x32_bf16 v[88:91], v[234:237], v[88:91], v[96:99]
	s_nop 3
	ds_read_b128 v[92:95], v190 offset:448
	v_or_b32_e32 v136, 0x70, v189
	v_or_b32_e32 v137, 0x71, v189
	v_or_b32_e32 v138, 0x72, v189
	v_or_b32_e32 v139, 0x73, v189
	v_cmp_le_i32_e64 s[16:17], v136, v188
	v_cmp_le_i32_e64 s[18:19], v137, v188
	v_cmp_le_i32_e64 s[54:55], v138, v188
	v_cmp_le_i32_e64 s[50:51], v139, v188
	s_cbranch_vccnz .Lmk_done_7
	v_cndmask_b32_e64 v140, 1, 0, s[42:43]
	v_add_u32_e32 v140, v140, v188
	v_cmp_ge_i32_e64 s[16:17], v136, v140
	v_cmp_ge_i32_e64 s[18:19], v137, v140
	v_cmp_ge_i32_e64 s[54:55], v138, v140
	v_cmp_ge_i32_e64 s[50:51], v139, v140
